# h3 + batched adaLN modulation loads in norm_panels prologue
# speedup vs baseline: 1.0028x; 1.0028x over previous
; #define NORM_B_LOAD_MOD(b) f32x4 scv[2][2], shv[2][2]; _Pragma("unroll") for (int j = 0; j < 2; ++j) _Pragma("unroll") for (int n = 0; n < 2; ++n) { \
;         scv[j][n] = *(const f32x4*)(scale + (size_t)(b) * 6144 + 8 * lane + 512 * j + 4 * n) + 1.0f; shv[j][n] = *(const f32x4*)(shift + (size_t)(b) * 6144 + 8 * lane + 512 * j + 4 * n); }
; __device__ __forceinline__ void norm_panels(const bf16* xb, const float* gain, const float* shift, const float* scale, bf16* H, int bid, int G) {
;     ...
;     for (int pm = bid; pm < 256; pm += G) {
;         NORM_B_LOAD_MOD(pm >> 3)
.LBB0_1045:
	s_ashr_i32 s5, s4, 31
	s_lshl_b64 s[0:1], s[4:5], 11
	s_ashr_i32 s5, s6, 3
	v_lshl_add_u64 v[40:41], v[38:39], 0, s[0:1]
	v_mad_i64_i32 v[30:31], s[0:1], s5, v252, v[34:35]
	flat_load_dwordx4 v[150:153], v[30:31]
	v_mad_i64_i32 v[58:59], s[0:1], s5, v252, v[36:37]
	s_mov_b32 s5, -4
	s_mov_b32 s10, 0x358637bd
	s_mov_b64 s[12:13], 0x2000
	flat_load_dwordx4 v[154:157], v[30:31] offset:16
	flat_load_dwordx4 v[158:161], v[30:31] offset:2048
	flat_load_dwordx4 v[162:165], v[30:31] offset:2064
	flat_load_dwordx4 v[18:21], v[58:59]
	flat_load_dwordx4 v[22:25], v[58:59] offset:16
	flat_load_dwordx4 v[26:29], v[58:59] offset:2048
	s_nop 0
	flat_load_dwordx4 v[30:33], v[58:59] offset:2064
	s_waitcnt vmcnt(0) lgkmcnt(0)
	v_pk_add_f32 v[42:43], v[152:153], 1.0 op_sel_hi:[1,0]
	v_pk_add_f32 v[44:45], v[150:151], 1.0 op_sel_hi:[1,0]
	v_pk_add_f32 v[46:47], v[156:157], 1.0 op_sel_hi:[1,0]
	v_pk_add_f32 v[48:49], v[154:155], 1.0 op_sel_hi:[1,0]
	v_pk_add_f32 v[50:51], v[160:161], 1.0 op_sel_hi:[1,0]
	v_pk_add_f32 v[52:53], v[158:159], 1.0 op_sel_hi:[1,0]
	v_pk_add_f32 v[54:55], v[164:165], 1.0 op_sel_hi:[1,0]
	v_pk_add_f32 v[56:57], v[162:163], 1.0 op_sel_hi:[1,0]
